# adds: attention units 2 and 4 of each wave take the neighbouring query group, so every wave gets two even and two odd query groups (evens walk more key tiles)
# baseline (speedup 1.0000x reference)
; __device__ __forceinline__ void sb_attn_wave(const bf16_t* __restrict__ P, const bf16_t* __restrict__ KHp, const bf16_t* __restrict__ Vt, bf16_t* __restrict__ mixed, int gw, int NGW, int lane, LAS unsigned char* wl) {
;     ...
;         const int un = u + NGW; const bool hn = un < NUNITS;
;         if (hn) { u = un; SB_UNIT_SETUP(u); }
.LBB0_418:
	s_add_i32 s50, s49, s76
	s_cmpk_gt_i32 s50, 0x1fff
	s_cselect_b64 s[4:5], -1, 0
	s_and_b64 vcc, exec, s[4:5]
	s_mov_b32 s22, s39
	s_mov_b32 s23, s48
	s_mov_b64 s[8:9], s[0:1]
	s_cbranch_vccnz .LBB0_407
	s_bfe_u32 s100, s50, 0x1000b
	s_xor_b32 s100, s50, s100
	s_ashr_i32 s8, s100, 10
	s_ashr_i32 s9, s8, 31
	s_lshl_b32 s38, s100, 5
	s_lshl_b64 s[8:9], s[8:9], 12
	s_and_b32 s23, s38, 0xfe0
	s_or_b32 s12, s8, s23
	s_ashr_i32 s52, s100, 7
	v_mov_b32_e32 v33, s9
	v_or_b32_e32 v32, s12, v144
	s_and_b32 s22, s52, 7
	v_lshlrev_b64 v[32:33], 12, v[32:33]
	v_lshl_add_u64 v[32:33], s[16:17], 0, v[32:33]
	s_lshl_b32 s12, s22, 7
	s_ashr_i32 s53, s52, 31
	v_lshl_add_u64 v[32:33], v[32:33], 0, s[12:13]
	v_lshlrev_b32_e32 v34, 1, v146
	v_mov_b32_e32 v35, v193
	s_lshl_b64 s[52:53], s[52:53], 19
	s_bfe_u32 s38, s38, 0x60006
	v_lshl_add_u64 v[32:33], v[32:33], 0, v[34:35]
	v_lshl_add_u64 v[154:155], v[148:149], 0, s[52:53]
	s_lshl_b32 s12, s38, 13
	global_load_dwordx4 v[64:67], v[32:33], off
	global_load_dwordx4 v[68:71], v[32:33], off offset:32
	global_load_dwordx4 v[72:75], v[32:33], off offset:64
	global_load_dwordx4 v[76:79], v[32:33], off offset:96
	v_lshl_add_u64 v[32:33], v[154:155], 0, s[12:13]
	s_movk_i32 s3, 0x1000
	global_load_dwordx4 v[80:83], v[32:33], off
	global_load_dwordx4 v[84:87], v[32:33], off offset:1024
	global_load_dwordx4 v[88:91], v[32:33], off offset:2048
	global_load_dwordx4 v[92:95], v[32:33], off offset:3072
	v_add_co_u32_e32 v32, vcc, s3, v32
	v_lshl_add_u64 v[152:153], v[150:151], 0, s[52:53]
	s_nop 0
	v_addc_co_u32_e32 v33, vcc, 0, v33, vcc
	global_load_dwordx4 v[96:99], v[32:33], off
	global_load_dwordx4 v[100:103], v[32:33], off offset:1024
	global_load_dwordx4 v[104:107], v[32:33], off offset:2048
	global_load_dwordx4 v[108:111], v[32:33], off offset:3072
	v_lshl_add_u64 v[32:33], v[152:153], 0, s[12:13]
	global_load_dwordx4 v[112:115], v[32:33], off
	global_load_dwordx4 v[116:119], v[32:33], off offset:1024
	global_load_dwordx4 v[120:123], v[32:33], off offset:2048
	global_load_dwordx4 v[124:127], v[32:33], off offset:3072
	v_add_co_u32_e32 v32, vcc, 0x1000, v32
	s_mov_b32 s49, s50
	s_nop 0
	v_addc_co_u32_e32 v33, vcc, 0, v33, vcc
	global_load_dwordx4 v[128:131], v[32:33], off
	global_load_dwordx4 v[132:135], v[32:33], off offset:1024
	global_load_dwordx4 v[136:139], v[32:33], off offset:2048
	global_load_dwordx4 v[140:143], v[32:33], off offset:3072
	s_branch .LBB0_407
